# v42 plus one static s_setprio 1 for waves 0-3 during the diff-attention phases (strategy 7.4, other half)
# speedup vs baseline: 1.0000x; 1.0000x over previous
;     ...
;         if (wave >= 4) __builtin_amdgcn_s_setprio(1);
.LBB0_787:
	s_or_b64 exec, exec, s[10:11]
	s_mov_b64 s[46:47], s[96:97]
	s_waitcnt lgkmcnt(0)
	v_mov_b32_e32 v0, v201
	s_barrier
	v_readlane_b32 s98, v252, 1
	s_nop 3
	s_cmp_ge_u32 s98, 4
	s_cbranch_scc1 .Lattn_prio_a
	s_setprio 1

;     ...
;         if (wave >= 4) __builtin_amdgcn_s_setprio(1);
.LBB0_1831:
	s_or_b64 exec, exec, s[6:7]
	v_readlane_b32 s44, v252, 15
	v_readlane_b32 s45, v252, 16
	s_waitcnt lgkmcnt(0)
	v_mov_b32_e32 v0, v201
	s_barrier
	v_readlane_b32 s98, v252, 1
	s_nop 3
	s_cmp_ge_u32 s98, 4
	s_cbranch_scc1 .Lattn_prio_b
	s_setprio 1
